# mixer-A loop tail: exit test issued before the DMA-landed wait (identical byte layout)
# speedup vs baseline: 1.0103x; 1.0008x over previous
.Lattn_dma_done_a:
	v_exp_f32_e32 v172, v128
	v_exp_f32_e32 v170, v129
	v_exp_f32_e32 v176, v130
	v_exp_f32_e32 v168, v131
	v_exp_f32_e32 v182, v132
	v_exp_f32_e32 v178, v133
	v_exp_f32_e32 v188, v134
	v_exp_f32_e32 v174, v135
	v_exp_f32_e32 v192, v136
	v_exp_f32_e32 v186, v137
	v_exp_f32_e32 v194, v138
	v_exp_f32_e32 v180, v139
	v_exp_f32_e32 v196, v140
	v_exp_f32_e32 v190, v141
	v_exp_f32_e32 v198, v142
	v_exp_f32_e32 v184, v143
	v_cvt_pk_bf16_f32 v144, v173, v169
	v_cvt_pk_bf16_f32 v145, v177, v171
	v_cvt_pk_bf16_f32 v146, v183, v175
	v_cvt_pk_bf16_f32 v147, v189, v179
	v_cvt_pk_bf16_f32 v148, v193, v181
	v_cvt_pk_bf16_f32 v149, v195, v187
	v_cvt_pk_bf16_f32 v150, v197, v185
	v_cvt_pk_bf16_f32 v151, v199, v191
	v_cvt_pk_bf16_f32 v128, v172, v170
	v_cvt_pk_bf16_f32 v129, v176, v168
	v_cvt_pk_bf16_f32 v130, v182, v178
	v_cvt_pk_bf16_f32 v131, v188, v174
	v_cvt_pk_bf16_f32 v132, v192, v186
	v_cvt_pk_bf16_f32 v133, v194, v180
	v_cvt_pk_bf16_f32 v134, v196, v190
	v_cvt_pk_bf16_f32 v135, v198, v184
	v_add3_u32 v160, s7, v162, v160
	v_xad_u32 v252, v163, 64, s7
	v_add_u32_e32 v203, s7, v203
	v_add_u32_e32 v205, s7, v206
	ds_read_b64_tr_b16 v[136:137], v160 offset:32768
	ds_read_b64_tr_b16 v[138:139], v160 offset:34816
	ds_read_b64_tr_b16 v[140:141], v160 offset:36864
	ds_read_b64_tr_b16 v[142:143], v160 offset:38912
	ds_read_b64_tr_b16 v[152:153], v252 offset:32768
	ds_read_b64_tr_b16 v[154:155], v252 offset:34816
	ds_read_b64_tr_b16 v[156:157], v252 offset:36864
	ds_read_b64_tr_b16 v[158:159], v252 offset:38912
	ds_read_b64_tr_b16 v[208:209], v203 offset:32768
	ds_read_b64_tr_b16 v[210:211], v203 offset:34816
	ds_read_b64_tr_b16 v[212:213], v203 offset:36864
	ds_read_b64_tr_b16 v[214:215], v203 offset:38912
	ds_read_b64_tr_b16 v[216:217], v205 offset:32768
	ds_read_b64_tr_b16 v[218:219], v205 offset:34816
	ds_read_b64_tr_b16 v[220:221], v205 offset:36864
	ds_read_b64_tr_b16 v[222:223], v205 offset:38912
	s_waitcnt lgkmcnt(14)
	v_mfma_f32_32x32x16_bf16 v[64:79], v[144:147], v[136:139], v[64:79]
	v_mfma_f32_32x32x16_bf16 v[0:15], v[128:131], v[136:139], v[0:15]
	s_waitcnt lgkmcnt(10)
	v_mfma_f32_32x32x16_bf16 v[80:95], v[144:147], v[152:155], v[80:95]
	v_mfma_f32_32x32x16_bf16 v[16:31], v[128:131], v[152:155], v[16:31]
	s_waitcnt lgkmcnt(6)
	v_mfma_f32_32x32x16_bf16 v[96:111], v[144:147], v[208:211], v[96:111]
	v_mfma_f32_32x32x16_bf16 v[32:47], v[128:131], v[208:211], v[32:47]
	s_waitcnt lgkmcnt(2)
	v_mfma_f32_32x32x16_bf16 v[112:127], v[144:147], v[216:219], v[112:127]
	v_mfma_f32_32x32x16_bf16 v[48:63], v[128:131], v[216:219], v[48:63]
	v_mfma_f32_32x32x16_bf16 v[64:79], v[148:151], v[140:143], v[64:79]
	v_mfma_f32_32x32x16_bf16 v[0:15], v[132:135], v[140:143], v[0:15]
	v_mfma_f32_32x32x16_bf16 v[80:95], v[148:151], v[156:159], v[80:95]
	v_mfma_f32_32x32x16_bf16 v[16:31], v[132:135], v[156:159], v[16:31]
	v_mfma_f32_32x32x16_bf16 v[96:111], v[148:151], v[212:215], v[96:111]
	v_mfma_f32_32x32x16_bf16 v[32:47], v[132:135], v[212:215], v[32:47]
	s_waitcnt lgkmcnt(0)
	v_mfma_f32_32x32x16_bf16 v[112:127], v[148:151], v[220:223], v[112:127]
	v_mfma_f32_32x32x16_bf16 v[48:63], v[132:135], v[220:223], v[48:63]
	ds_read_b128 v[128:131], v207 offset:4096
	ds_read_b128 v[132:135], v224
	ds_read_b128 v[136:139], v225 offset:4096
	ds_read_b128 v[140:143], v226
	s_waitcnt lgkmcnt(2)
	v_mfma_f32_32x32x16_bf16 v[144:159], v[128:131], v[132:135], 0
	ds_read_b128 v[128:131], v227 offset:4096
	ds_read_b128 v[132:135], v228
	s_waitcnt lgkmcnt(2)
	v_mfma_f32_32x32x16_bf16 v[144:159], v[136:139], v[140:143], v[144:159]
	ds_read_b128 v[136:139], v230 offset:4096
	ds_read_b128 v[140:143], v232
	s_waitcnt lgkmcnt(2)
	v_mfma_f32_32x32x16_bf16 v[144:159], v[128:131], v[132:135], v[144:159]
	ds_read_b128 v[128:131], v207 offset:12288
	ds_read_b128 v[132:135], v224 offset:4096
	s_waitcnt lgkmcnt(2)
	v_mfma_f32_32x32x16_bf16 v[144:159], v[136:139], v[140:143], v[144:159]
	ds_read_b128 v[208:211], v225 offset:12288
	ds_read_b128 v[212:215], v226 offset:4096
	s_waitcnt lgkmcnt(2)
	v_mfma_f32_32x32x16_bf16 v[128:143], v[128:131], v[132:135], 0
	s_nop 7
	v_exp_f32_e32 v229, v144
	v_exp_f32_e32 v145, v145
	v_exp_f32_e32 v231, v146
	v_exp_f32_e32 v147, v147
	ds_read_b128 v[216:219], v227 offset:12288
	ds_read_b128 v[220:223], v228 offset:4096
	s_waitcnt lgkmcnt(2)
	v_mfma_f32_32x32x16_bf16 v[128:143], v[208:211], v[212:215], v[128:143]
	v_exp_f32_e32 v233, v148
	v_exp_f32_e32 v235, v149
	v_exp_f32_e32 v237, v150
	v_exp_f32_e32 v239, v151
	ds_read_b128 v[148:151], v230 offset:12288
	ds_read_b128 v[208:211], v232 offset:4096
	s_waitcnt lgkmcnt(2)
	v_mfma_f32_32x32x16_bf16 v[128:143], v[216:219], v[220:223], v[128:143]
	v_exp_f32_e32 v241, v152
	v_exp_f32_e32 v243, v153
	v_exp_f32_e32 v245, v154
	v_exp_f32_e32 v247, v155
	s_waitcnt lgkmcnt(0)
	v_mfma_f32_32x32x16_bf16 v[128:143], v[148:151], v[208:211], v[128:143]
	v_exp_f32_e32 v249, v156
	v_exp_f32_e32 v251, v157
	v_exp_f32_e32 v207, v158
	v_exp_f32_e32 v163, v159
	s_nop 7
	v_exp_f32_e32 v228, v128
	v_exp_f32_e32 v146, v129
	v_exp_f32_e32 v230, v130
	v_exp_f32_e32 v144, v131
	v_exp_f32_e32 v232, v132
	v_exp_f32_e32 v238, v133
	v_exp_f32_e32 v236, v134
	v_exp_f32_e32 v234, v135
	v_exp_f32_e32 v240, v136
	v_exp_f32_e32 v246, v137
	v_exp_f32_e32 v244, v138
	v_exp_f32_e32 v242, v139
	v_exp_f32_e32 v248, v140
	v_exp_f32_e32 v162, v141
	v_exp_f32_e32 v206, v142
	v_exp_f32_e32 v250, v143
	v_cvt_pk_bf16_f32 v148, v229, v145
	v_cvt_pk_bf16_f32 v149, v231, v147
	v_cvt_pk_bf16_f32 v150, v233, v235
	v_cvt_pk_bf16_f32 v151, v237, v239
	v_cvt_pk_bf16_f32 v152, v241, v243
	v_cvt_pk_bf16_f32 v153, v245, v247
	v_cvt_pk_bf16_f32 v154, v249, v251
	v_cvt_pk_bf16_f32 v155, v207, v163
	v_cvt_pk_bf16_f32 v128, v228, v146
	v_cvt_pk_bf16_f32 v129, v230, v144
	v_cvt_pk_bf16_f32 v130, v232, v238
	v_cvt_pk_bf16_f32 v131, v236, v234
	v_cvt_pk_bf16_f32 v132, v240, v246
	v_cvt_pk_bf16_f32 v133, v244, v242
	v_cvt_pk_bf16_f32 v134, v248, v162
	v_cvt_pk_bf16_f32 v135, v206, v250
	s_addk_i32 s5, 0x4000
	s_add_i32 s4, s4, 0x10000
	s_and_b32 s7, s5, 0x4000
	ds_read_b64_tr_b16 v[136:137], v160 offset:40960
	ds_read_b64_tr_b16 v[138:139], v160 offset:43008
	ds_read_b64_tr_b16 v[140:141], v160 offset:45056
	ds_read_b64_tr_b16 v[142:143], v160 offset:47104
	ds_read_b64_tr_b16 v[156:157], v252 offset:40960
	ds_read_b64_tr_b16 v[158:159], v252 offset:43008
	ds_read_b64_tr_b16 v[208:209], v252 offset:45056
	ds_read_b64_tr_b16 v[210:211], v252 offset:47104
	ds_read_b64_tr_b16 v[212:213], v203 offset:40960
	ds_read_b64_tr_b16 v[214:215], v203 offset:43008
	ds_read_b64_tr_b16 v[216:217], v203 offset:45056
	ds_read_b64_tr_b16 v[218:219], v203 offset:47104
	ds_read_b64_tr_b16 v[220:221], v205 offset:40960
	ds_read_b64_tr_b16 v[222:223], v205 offset:43008
	ds_read_b64_tr_b16 v[224:225], v205 offset:45056
	ds_read_b64_tr_b16 v[226:227], v205 offset:47104
	s_waitcnt lgkmcnt(14)
	v_mfma_f32_32x32x16_bf16 v[64:79], v[148:151], v[136:139], v[64:79]
	v_mfma_f32_32x32x16_bf16 v[0:15], v[128:131], v[136:139], v[0:15]
	s_waitcnt lgkmcnt(10)
	v_mfma_f32_32x32x16_bf16 v[80:95], v[148:151], v[156:159], v[80:95]
	v_mfma_f32_32x32x16_bf16 v[16:31], v[128:131], v[156:159], v[16:31]
	s_waitcnt lgkmcnt(6)
	v_mfma_f32_32x32x16_bf16 v[96:111], v[148:151], v[212:215], v[96:111]
	v_mfma_f32_32x32x16_bf16 v[32:47], v[128:131], v[212:215], v[32:47]
	s_waitcnt lgkmcnt(2)
	v_mfma_f32_32x32x16_bf16 v[112:127], v[148:151], v[220:223], v[112:127]
	v_mfma_f32_32x32x16_bf16 v[48:63], v[128:131], v[220:223], v[48:63]
	v_add_f32_e64 v128, v172, v176
	v_add_f32_e64 v129, v173, v177
	v_add_f32_e64 v130, v168, v170
	v_add_f32_e64 v131, v169, v171
	v_pk_add_f32 v[136:137], v[182:183], v[188:189]
	v_pk_add_f32 v[128:129], v[136:137], v[128:129]
	v_pk_add_f32 v[136:137], v[174:175], v[178:179]
	v_pk_add_f32 v[138:139], v[232:233], v[236:237]
	v_pk_add_f32 v[130:131], v[136:137], v[130:131]
	v_pk_add_f32 v[136:137], v[192:193], v[194:195]
	v_mfma_f32_32x32x16_bf16 v[64:79], v[152:155], v[140:143], v[64:79]
	v_add_f32_e64 v128, v136, v128
	v_add_f32_e64 v129, v137, v129
	v_add_f32_e64 v136, v180, v186
	v_add_f32_e64 v137, v181, v187
	v_add_f32_e64 v130, v136, v130
	v_add_f32_e64 v131, v137, v131
	v_pk_add_f32 v[136:137], v[196:197], v[198:199]
	s_nop 0
	v_pk_add_f32 v[128:129], v[136:137], v[128:129]
	v_pk_add_f32 v[136:137], v[184:185], v[190:191]
	v_mfma_f32_32x32x16_bf16 v[0:15], v[132:135], v[140:143], v[0:15]
	v_add_f32_e64 v130, v136, v130
	v_add_f32_e64 v131, v137, v131
	v_add_f32_e64 v136, v144, v146
	v_add_f32_e64 v137, v145, v147
	v_add_f32_e64 v128, v128, v130
	v_add_f32_e64 v129, v129, v131
	v_pk_add_f32 v[130:131], v[228:229], v[230:231]
	v_pk_add_f32 v[128:129], v[166:167], v[128:129]
	v_mfma_f32_32x32x16_bf16 v[80:95], v[152:155], v[208:211], v[80:95]
	v_add_f32_e64 v130, v138, v130
	v_add_f32_e64 v131, v139, v131
	v_add_f32_e64 v138, v234, v238
	v_add_f32_e64 v139, v235, v239
	v_add_f32_e64 v136, v138, v136
	v_add_f32_e64 v137, v139, v137
	v_pk_add_f32 v[138:139], v[240:241], v[244:245]
	s_nop 0
	v_pk_add_f32 v[130:131], v[138:139], v[130:131]
	v_mfma_f32_32x32x16_bf16 v[16:31], v[132:135], v[208:211], v[16:31]
	v_add_f32_e64 v138, v242, v246
	v_add_f32_e64 v139, v243, v247
	v_add_f32_e64 v136, v138, v136
	v_add_f32_e64 v137, v139, v137
	v_add_f32_e64 v138, v248, v206
	v_add_f32_e64 v139, v249, v207
	v_pk_add_f32 v[130:131], v[138:139], v[130:131]
	v_pk_add_f32 v[138:139], v[250:251], v[162:163]
	v_mfma_f32_32x32x16_bf16 v[96:111], v[152:155], v[216:219], v[96:111]
	v_add_f32_e64 v136, v138, v136
	v_add_f32_e64 v137, v139, v137
	v_add_f32_e64 v130, v130, v136
	v_add_f32_e64 v131, v131, v137
	v_add_f32_e64 v166, v128, v130
	v_add_f32_e64 v167, v129, v131
	v_mfma_f32_32x32x16_bf16 v[32:47], v[132:135], v[216:219], v[32:47]
	s_waitcnt lgkmcnt(0)
	v_mfma_f32_32x32x16_bf16 v[112:127], v[152:155], v[224:227], v[112:127]
	v_mfma_f32_32x32x16_bf16 v[48:63], v[132:135], v[224:227], v[48:63]
	s_cmp_eq_u32 s4, 0x400000
	s_waitcnt vmcnt(0)
	s_cbranch_scc0 .Lattn_head_a
	s_barrier
